# early L1 invalidate + barrier leader's workspace-pointer load issued before the arrival barrier
# speedup vs baseline: 1.0015x; 1.0015x over previous
; #define LAS __attribute__((address_space(3)))
; DI int lane_id() { int l = __builtin_amdgcn_mbcnt_hi(-1, __builtin_amdgcn_mbcnt_lo(-1, 0)); asm volatile("" : "+v"(l)); return l; }
; DI unsigned xb_ld(unsigned* q) { return __hip_atomic_load(q, __ATOMIC_RELAXED, __HIP_MEMORY_SCOPE_AGENT); }
; DI unsigned xb_xcc_id() { return (unsigned)__builtin_amdgcn_s_getreg((3 << 11) | 20) & 0xFu; }
; DI void xcd_barrier_complete(unsigned* bar, unsigned x, unsigned& nloc, unsigned& nx) {
;     ...
;         sum = 0u; cnt = 0u; mine = 0u;
; #pragma unroll
;         for (unsigned j = 0; j < 16; ++j) { const unsigned c = xb_ld(&bar[XB_XCNT(j)]); sum += c; cnt += (c > 0u) ? 1u : 0u; mine = (j == x) ? c : mine; }
; DI void grid_bar(unsigned* bar, volatile LAS unsigned* st, int wid) {
;     asm volatile("s_waitcnt vmcnt(0)" ::: "memory");
;     __syncthreads();
;     if (wid == 0) {
;         if (lane_id() == 0) {
;             __builtin_amdgcn_s_waitcnt(0);
;             const unsigned x = xb_xcc_id();
;             unsigned nloc = st[0], nx = st[1];
;             if (nloc == 0u) { xcd_barrier_complete(bar, x, nloc, nx); st[0] = nloc; st[1] = nx; }
.LBB0_241:
	s_cmp_gt_i32 s35, 1
	s_cselect_b64 s[2:3], -1, 0
	s_and_b64 s[4:5], s[36:37], s[2:3]
	s_andn2_b64 vcc, exec, s[4:5]
	s_cbranch_vccnz .LBB0_297
	s_load_dwordx2 s[8:9], s[0:1], 0xa8
	s_waitcnt vmcnt(0)
	s_cmp_gt_u32 s88, 63
	s_barrier
	s_cbranch_scc1 .LBB0_296
	v_mbcnt_hi_u32_b32 v0, -1, v254
	s_nop 0
	v_cmp_eq_u32_e32 vcc, 0, v0
	s_and_saveexec_b64 s[4:5], vcc
	s_cbranch_execz .LBB0_295
	s_add_i32 s11, 0, 0x20000
	v_mov_b32_e32 v0, s11
	s_waitcnt vmcnt(0) expcnt(0) lgkmcnt(0)
	s_getreg_b32 s10, hwreg(HW_REG_XCC_ID, 0, 4)
	ds_read_b32 v2, v0
	s_add_i32 s11, 0, 0x20004
	v_mov_b32_e32 v0, s11
	ds_read_b32 v0, v0
	s_and_b32 s54, s10, 15
	s_waitcnt lgkmcnt(1)
	v_cmp_ne_u32_e32 vcc, 0, v2
	s_cbranch_vccnz .LBB0_259
	s_add_u32 s10, s8, 0xcd80200
	s_addc_u32 s11, s9, 0
	s_add_u32 s12, s8, 0xcd80400
	s_addc_u32 s13, s9, 0
	s_add_u32 s14, s8, 0xcd80500
	s_addc_u32 s15, s9, 0
	s_add_u32 s16, s8, 0xcd80600
	s_addc_u32 s17, s9, 0
	s_add_u32 s18, s8, 0xcd80700
	s_addc_u32 s19, s9, 0
	s_add_u32 s20, s8, 0xcd80800
	s_addc_u32 s21, s9, 0
	s_add_u32 s22, s8, 0xcd80900
	s_addc_u32 s23, s9, 0
	s_add_u32 s24, s8, 0xcd80a00
	s_addc_u32 s25, s9, 0
	s_add_u32 s26, s8, 0xcd80b00
	s_addc_u32 s27, s9, 0
	s_add_u32 s28, s8, 0xcd80c00
	s_addc_u32 s29, s9, 0
	s_add_u32 s30, s8, 0xcd80d00
	s_addc_u32 s31, s9, 0
	s_add_u32 s36, s8, 0xcd80e00
	s_addc_u32 s37, s9, 0
	s_add_u32 s38, s8, 0xcd80f00
	s_addc_u32 s39, s9, 0
	s_add_u32 s40, s8, 0xcd81000
	s_addc_u32 s41, s9, 0
	s_add_u32 s42, s8, 0xcd81100
	s_addc_u32 s43, s9, 0
	s_add_u32 s44, s8, 0xcd81200
	s_addc_u32 s45, s9, 0
	s_add_u32 s46, s8, 0xcd81300
	s_addc_u32 s47, s9, 0
	s_mov_b32 s55, 1
	v_mov_b32_e32 v16, 0
	s_branch .LBB0_247

; #define LAS __attribute__((address_space(3)))
; DI int lane_id() { int l = __builtin_amdgcn_mbcnt_hi(-1, __builtin_amdgcn_mbcnt_lo(-1, 0)); asm volatile("" : "+v"(l)); return l; }
; DI unsigned xb_ld(unsigned* q) { return __hip_atomic_load(q, __ATOMIC_RELAXED, __HIP_MEMORY_SCOPE_AGENT); }
; DI unsigned xb_xcc_id() { return (unsigned)__builtin_amdgcn_s_getreg((3 << 11) | 20) & 0xFu; }
; DI void xcd_barrier_complete(unsigned* bar, unsigned x, unsigned& nloc, unsigned& nx) {
;     ...
;         sum = 0u; cnt = 0u; mine = 0u;
; #pragma unroll
;         for (unsigned j = 0; j < 16; ++j) { const unsigned c = xb_ld(&bar[XB_XCNT(j)]); sum += c; cnt += (c > 0u) ? 1u : 0u; mine = (j == x) ? c : mine; }
; DI void grid_bar(unsigned* bar, volatile LAS unsigned* st, int wid) {
;     asm volatile("s_waitcnt vmcnt(0)" ::: "memory");
;     __syncthreads();
;     if (wid == 0) {
;         if (lane_id() == 0) {
;             __builtin_amdgcn_s_waitcnt(0);
;             const unsigned x = xb_xcc_id();
;             unsigned nloc = st[0], nx = st[1];
;             if (nloc == 0u) { xcd_barrier_complete(bar, x, nloc, nx); st[0] = nloc; st[1] = nx; }
.Lconv_skip_0:
	s_cmp_gt_i32 s35, 2
	s_cselect_b64 s[2:3], -1, 0
	s_and_b64 s[4:5], s[8:9], s[2:3]
	s_andn2_b64 vcc, exec, s[4:5]
	s_cbranch_vccnz .LBB0_454
	s_load_dwordx2 s[8:9], s[0:1], 0xa8
	s_waitcnt vmcnt(0)
	s_cmp_gt_u32 s88, 63
	s_waitcnt vmcnt(0) lgkmcnt(0)
	s_barrier
	s_cbranch_scc1 .LBB0_453
	v_mbcnt_hi_u32_b32 v0, -1, v254
	s_nop 0
	v_cmp_eq_u32_e32 vcc, 0, v0
	s_and_saveexec_b64 s[4:5], vcc
	s_cbranch_execz .LBB0_452
	s_add_i32 s11, 0, 0x20000
	v_mov_b32_e32 v0, s11
	s_waitcnt vmcnt(0) expcnt(0) lgkmcnt(0)
	s_getreg_b32 s10, hwreg(HW_REG_XCC_ID, 0, 4)
	ds_read_b32 v2, v0
	s_add_i32 s11, 0, 0x20004
	v_mov_b32_e32 v0, s11
	ds_read_b32 v0, v0
	s_and_b32 s54, s10, 15
	s_waitcnt lgkmcnt(1)
	v_cmp_ne_u32_e32 vcc, 0, v2
	s_cbranch_vccnz .LBB0_416
	s_add_u32 s10, s8, 0xcd80200
	s_addc_u32 s11, s9, 0
	s_add_u32 s12, s8, 0xcd80400
	s_addc_u32 s13, s9, 0
	s_add_u32 s14, s8, 0xcd80500
	s_addc_u32 s15, s9, 0
	s_add_u32 s16, s8, 0xcd80600
	s_addc_u32 s17, s9, 0
	s_add_u32 s18, s8, 0xcd80700
	s_addc_u32 s19, s9, 0
	s_add_u32 s20, s8, 0xcd80800
	s_addc_u32 s21, s9, 0
	s_add_u32 s22, s8, 0xcd80900
	s_addc_u32 s23, s9, 0
	s_add_u32 s24, s8, 0xcd80a00
	s_addc_u32 s25, s9, 0
	s_add_u32 s26, s8, 0xcd80b00
	s_addc_u32 s27, s9, 0
	s_add_u32 s28, s8, 0xcd80c00
	s_addc_u32 s29, s9, 0
	s_add_u32 s30, s8, 0xcd80d00
	s_addc_u32 s31, s9, 0
	s_add_u32 s36, s8, 0xcd80e00
	s_addc_u32 s37, s9, 0
	s_add_u32 s38, s8, 0xcd80f00
	s_addc_u32 s39, s9, 0
	s_add_u32 s40, s8, 0xcd81000
	s_addc_u32 s41, s9, 0
	s_add_u32 s42, s8, 0xcd81100
	s_addc_u32 s43, s9, 0
	s_add_u32 s44, s8, 0xcd81200
	s_addc_u32 s45, s9, 0
	s_add_u32 s46, s8, 0xcd81300
	s_addc_u32 s47, s9, 0
	s_mov_b32 s55, 1
	v_mov_b32_e32 v16, 0
	s_branch .LBB0_404

; #define LAS __attribute__((address_space(3)))
; DI int lane_id() { int l = __builtin_amdgcn_mbcnt_hi(-1, __builtin_amdgcn_mbcnt_lo(-1, 0)); asm volatile("" : "+v"(l)); return l; }
; DI unsigned xb_ld(unsigned* q) { return __hip_atomic_load(q, __ATOMIC_RELAXED, __HIP_MEMORY_SCOPE_AGENT); }
; DI unsigned xb_xcc_id() { return (unsigned)__builtin_amdgcn_s_getreg((3 << 11) | 20) & 0xFu; }
; DI void xcd_barrier_complete(unsigned* bar, unsigned x, unsigned& nloc, unsigned& nx) {
;     ...
;         sum = 0u; cnt = 0u; mine = 0u;
; #pragma unroll
;         for (unsigned j = 0; j < 16; ++j) { const unsigned c = xb_ld(&bar[XB_XCNT(j)]); sum += c; cnt += (c > 0u) ? 1u : 0u; mine = (j == x) ? c : mine; }
; DI void grid_bar(unsigned* bar, volatile LAS unsigned* st, int wid) {
;     asm volatile("s_waitcnt vmcnt(0)" ::: "memory");
;     __syncthreads();
;     if (wid == 0) {
;         if (lane_id() == 0) {
;             __builtin_amdgcn_s_waitcnt(0);
;             const unsigned x = xb_xcc_id();
;             unsigned nloc = st[0], nx = st[1];
;             if (nloc == 0u) { xcd_barrier_complete(bar, x, nloc, nx); st[0] = nloc; st[1] = nx; }
.LBB0_471:
	s_cmp_gt_i32 s35, 3
	s_cselect_b64 s[2:3], -1, 0
	s_and_b64 s[4:5], s[16:17], s[2:3]
	s_andn2_b64 vcc, exec, s[4:5]
	s_cbranch_vccnz .LBB0_527
	s_load_dwordx2 s[8:9], s[0:1], 0xa8
	s_waitcnt vmcnt(0)
	s_cmp_gt_u32 s88, 63
	s_waitcnt vmcnt(0) lgkmcnt(0)
	s_barrier
	s_cbranch_scc1 .LBB0_526
	v_mbcnt_hi_u32_b32 v0, -1, v254
	s_nop 0
	v_cmp_eq_u32_e32 vcc, 0, v0
	s_and_saveexec_b64 s[4:5], vcc
	s_cbranch_execz .LBB0_525
	s_add_i32 s11, 0, 0x20000
	v_mov_b32_e32 v0, s11
	s_waitcnt vmcnt(0) expcnt(0) lgkmcnt(0)
	s_getreg_b32 s10, hwreg(HW_REG_XCC_ID, 0, 4)
	ds_read_b32 v2, v0
	s_add_i32 s11, 0, 0x20004
	v_mov_b32_e32 v0, s11
	ds_read_b32 v0, v0
	s_and_b32 s54, s10, 15
	s_waitcnt lgkmcnt(1)
	v_cmp_ne_u32_e32 vcc, 0, v2
	s_cbranch_vccnz .LBB0_489
	s_add_u32 s10, s8, 0xcd80200
	s_addc_u32 s11, s9, 0
	s_add_u32 s12, s8, 0xcd80400
	s_addc_u32 s13, s9, 0
	s_add_u32 s14, s8, 0xcd80500
	s_addc_u32 s15, s9, 0
	s_add_u32 s16, s8, 0xcd80600
	s_addc_u32 s17, s9, 0
	s_add_u32 s18, s8, 0xcd80700
	s_addc_u32 s19, s9, 0
	s_add_u32 s20, s8, 0xcd80800
	s_addc_u32 s21, s9, 0
	s_add_u32 s22, s8, 0xcd80900
	s_addc_u32 s23, s9, 0
	s_add_u32 s24, s8, 0xcd80a00
	s_addc_u32 s25, s9, 0
	s_add_u32 s26, s8, 0xcd80b00
	s_addc_u32 s27, s9, 0
	s_add_u32 s28, s8, 0xcd80c00
	s_addc_u32 s29, s9, 0
	s_add_u32 s30, s8, 0xcd80d00
	s_addc_u32 s31, s9, 0
	s_add_u32 s36, s8, 0xcd80e00
	s_addc_u32 s37, s9, 0
	s_add_u32 s38, s8, 0xcd80f00
	s_addc_u32 s39, s9, 0
	s_add_u32 s40, s8, 0xcd81000
	s_addc_u32 s41, s9, 0
	s_add_u32 s42, s8, 0xcd81100
	s_addc_u32 s43, s9, 0
	s_add_u32 s44, s8, 0xcd81200
	s_addc_u32 s45, s9, 0
	s_add_u32 s46, s8, 0xcd81300
	s_addc_u32 s47, s9, 0
	s_mov_b32 s55, 1
	v_mov_b32_e32 v16, 0
	s_branch .LBB0_477

; #define LAS __attribute__((address_space(3)))
; DI int lane_id() { int l = __builtin_amdgcn_mbcnt_hi(-1, __builtin_amdgcn_mbcnt_lo(-1, 0)); asm volatile("" : "+v"(l)); return l; }
; DI unsigned xb_ld(unsigned* q) { return __hip_atomic_load(q, __ATOMIC_RELAXED, __HIP_MEMORY_SCOPE_AGENT); }
; DI unsigned xb_xcc_id() { return (unsigned)__builtin_amdgcn_s_getreg((3 << 11) | 20) & 0xFu; }
; DI void xcd_barrier_complete(unsigned* bar, unsigned x, unsigned& nloc, unsigned& nx) {
;     ...
;         sum = 0u; cnt = 0u; mine = 0u;
; #pragma unroll
;         for (unsigned j = 0; j < 16; ++j) { const unsigned c = xb_ld(&bar[XB_XCNT(j)]); sum += c; cnt += (c > 0u) ? 1u : 0u; mine = (j == x) ? c : mine; }
; DI void grid_bar(unsigned* bar, volatile LAS unsigned* st, int wid) {
;     asm volatile("s_waitcnt vmcnt(0)" ::: "memory");
;     __syncthreads();
;     if (wid == 0) {
;         if (lane_id() == 0) {
;             __builtin_amdgcn_s_waitcnt(0);
;             const unsigned x = xb_xcc_id();
;             unsigned nloc = st[0], nx = st[1];
;             if (nloc == 0u) { xcd_barrier_complete(bar, x, nloc, nx); st[0] = nloc; st[1] = nx; }
.Lp2_skip:
	s_cmp_gt_i32 s35, 4
	s_cselect_b64 s[2:3], -1, 0
	s_and_b64 s[4:5], s[4:5], s[2:3]
	s_andn2_b64 vcc, exec, s[4:5]
	s_cbranch_vccnz .LBB0_602
	s_load_dwordx2 s[8:9], s[0:1], 0xa8
	s_waitcnt vmcnt(0)
	s_cmp_gt_u32 s88, 63
	s_waitcnt vmcnt(0) lgkmcnt(0)
	s_barrier
	s_cbranch_scc1 .LBB0_601
	v_mbcnt_hi_u32_b32 v0, -1, v254
	s_nop 0
	v_cmp_eq_u32_e32 vcc, 0, v0
	s_and_saveexec_b64 s[4:5], vcc
	s_cbranch_execz .LBB0_600
	s_add_i32 s11, 0, 0x20000
	v_mov_b32_e32 v0, s11
	s_waitcnt vmcnt(0) expcnt(0) lgkmcnt(0)
	s_getreg_b32 s10, hwreg(HW_REG_XCC_ID, 0, 4)
	ds_read_b32 v2, v0
	s_add_i32 s11, 0, 0x20004
	v_mov_b32_e32 v0, s11
	ds_read_b32 v0, v0
	s_and_b32 s54, s10, 15
	s_waitcnt lgkmcnt(1)
	v_cmp_ne_u32_e32 vcc, 0, v2
	s_cbranch_vccnz .LBB0_564
	s_add_u32 s10, s8, 0xcd80200
	s_addc_u32 s11, s9, 0
	s_add_u32 s12, s8, 0xcd80400
	s_addc_u32 s13, s9, 0
	s_add_u32 s14, s8, 0xcd80500
	s_addc_u32 s15, s9, 0
	s_add_u32 s16, s8, 0xcd80600
	s_addc_u32 s17, s9, 0
	s_add_u32 s18, s8, 0xcd80700
	s_addc_u32 s19, s9, 0
	s_add_u32 s20, s8, 0xcd80800
	s_addc_u32 s21, s9, 0
	s_add_u32 s22, s8, 0xcd80900
	s_addc_u32 s23, s9, 0
	s_add_u32 s24, s8, 0xcd80a00
	s_addc_u32 s25, s9, 0
	s_add_u32 s26, s8, 0xcd80b00
	s_addc_u32 s27, s9, 0
	s_add_u32 s28, s8, 0xcd80c00
	s_addc_u32 s29, s9, 0
	s_add_u32 s30, s8, 0xcd80d00
	s_addc_u32 s31, s9, 0
	s_add_u32 s36, s8, 0xcd80e00
	s_addc_u32 s37, s9, 0
	s_add_u32 s38, s8, 0xcd80f00
	s_addc_u32 s39, s9, 0
	s_add_u32 s40, s8, 0xcd81000
	s_addc_u32 s41, s9, 0
	s_add_u32 s42, s8, 0xcd81100
	s_addc_u32 s43, s9, 0
	s_add_u32 s44, s8, 0xcd81200
	s_addc_u32 s45, s9, 0
	s_add_u32 s46, s8, 0xcd81300
	s_addc_u32 s47, s9, 0
	s_mov_b32 s55, 1
	v_mov_b32_e32 v16, 0
	s_branch .LBB0_552

; #define LAS __attribute__((address_space(3)))
; DI int lane_id() { int l = __builtin_amdgcn_mbcnt_hi(-1, __builtin_amdgcn_mbcnt_lo(-1, 0)); asm volatile("" : "+v"(l)); return l; }
; DI unsigned xb_ld(unsigned* q) { return __hip_atomic_load(q, __ATOMIC_RELAXED, __HIP_MEMORY_SCOPE_AGENT); }
; DI unsigned xb_xcc_id() { return (unsigned)__builtin_amdgcn_s_getreg((3 << 11) | 20) & 0xFu; }
; DI void xcd_barrier_complete(unsigned* bar, unsigned x, unsigned& nloc, unsigned& nx) {
;     ...
;         sum = 0u; cnt = 0u; mine = 0u;
; #pragma unroll
;         for (unsigned j = 0; j < 16; ++j) { const unsigned c = xb_ld(&bar[XB_XCNT(j)]); sum += c; cnt += (c > 0u) ? 1u : 0u; mine = (j == x) ? c : mine; }
; DI void grid_bar(unsigned* bar, volatile LAS unsigned* st, int wid) {
;     asm volatile("s_waitcnt vmcnt(0)" ::: "memory");
;     __syncthreads();
;     if (wid == 0) {
;         if (lane_id() == 0) {
;             __builtin_amdgcn_s_waitcnt(0);
;             const unsigned x = xb_xcc_id();
;             unsigned nloc = st[0], nx = st[1];
;             if (nloc == 0u) { xcd_barrier_complete(bar, x, nloc, nx); st[0] = nloc; st[1] = nx; }
.LBB0_641:
	s_cmp_gt_i32 s35, 5
	s_cselect_b64 s[2:3], -1, 0
	s_and_b64 s[4:5], s[8:9], s[2:3]
	s_andn2_b64 vcc, exec, s[4:5]
	s_cbranch_vccnz .LBB0_697
	s_load_dwordx2 s[8:9], s[0:1], 0xa8
	s_waitcnt vmcnt(0)
	s_cmp_gt_u32 s88, 63
	s_waitcnt vmcnt(0) lgkmcnt(0)
	s_barrier
	s_cbranch_scc1 .LBB0_696
	v_mbcnt_hi_u32_b32 v0, -1, v254
	s_nop 0
	v_cmp_eq_u32_e32 vcc, 0, v0
	s_and_saveexec_b64 s[4:5], vcc
	s_cbranch_execz .LBB0_695
	s_add_i32 s11, 0, 0x20000
	v_mov_b32_e32 v0, s11
	s_waitcnt vmcnt(0) expcnt(0) lgkmcnt(0)
	s_getreg_b32 s10, hwreg(HW_REG_XCC_ID, 0, 4)
	ds_read_b32 v2, v0
	s_add_i32 s11, 0, 0x20004
	v_mov_b32_e32 v0, s11
	ds_read_b32 v0, v0
	s_and_b32 s54, s10, 15
	s_waitcnt lgkmcnt(1)
	v_cmp_ne_u32_e32 vcc, 0, v2
	s_cbranch_vccnz .LBB0_659
	s_add_u32 s10, s8, 0xcd80200
	s_addc_u32 s11, s9, 0
	s_add_u32 s12, s8, 0xcd80400
	s_addc_u32 s13, s9, 0
	s_add_u32 s14, s8, 0xcd80500
	s_addc_u32 s15, s9, 0
	s_add_u32 s16, s8, 0xcd80600
	s_addc_u32 s17, s9, 0
	s_add_u32 s18, s8, 0xcd80700
	s_addc_u32 s19, s9, 0
	s_add_u32 s20, s8, 0xcd80800
	s_addc_u32 s21, s9, 0
	s_add_u32 s22, s8, 0xcd80900
	s_addc_u32 s23, s9, 0
	s_add_u32 s24, s8, 0xcd80a00
	s_addc_u32 s25, s9, 0
	s_add_u32 s26, s8, 0xcd80b00
	s_addc_u32 s27, s9, 0
	s_add_u32 s28, s8, 0xcd80c00
	s_addc_u32 s29, s9, 0
	s_add_u32 s30, s8, 0xcd80d00
	s_addc_u32 s31, s9, 0
	s_add_u32 s36, s8, 0xcd80e00
	s_addc_u32 s37, s9, 0
	s_add_u32 s38, s8, 0xcd80f00
	s_addc_u32 s39, s9, 0
	s_add_u32 s40, s8, 0xcd81000
	s_addc_u32 s41, s9, 0
	s_add_u32 s42, s8, 0xcd81100
	s_addc_u32 s43, s9, 0
	s_add_u32 s44, s8, 0xcd81200
	s_addc_u32 s45, s9, 0
	s_add_u32 s46, s8, 0xcd81300
	s_addc_u32 s47, s9, 0
	s_mov_b32 s55, 1
	v_mov_b32_e32 v16, 0
	s_branch .LBB0_647

; #define LAS __attribute__((address_space(3)))
; DI int lane_id() { int l = __builtin_amdgcn_mbcnt_hi(-1, __builtin_amdgcn_mbcnt_lo(-1, 0)); asm volatile("" : "+v"(l)); return l; }
; DI unsigned xb_ld(unsigned* q) { return __hip_atomic_load(q, __ATOMIC_RELAXED, __HIP_MEMORY_SCOPE_AGENT); }
; DI unsigned xb_xcc_id() { return (unsigned)__builtin_amdgcn_s_getreg((3 << 11) | 20) & 0xFu; }
; DI void xcd_barrier_complete(unsigned* bar, unsigned x, unsigned& nloc, unsigned& nx) {
;     ...
;         sum = 0u; cnt = 0u; mine = 0u;
; #pragma unroll
;         for (unsigned j = 0; j < 16; ++j) { const unsigned c = xb_ld(&bar[XB_XCNT(j)]); sum += c; cnt += (c > 0u) ? 1u : 0u; mine = (j == x) ? c : mine; }
; DI void grid_bar(unsigned* bar, volatile LAS unsigned* st, int wid) {
;     asm volatile("s_waitcnt vmcnt(0)" ::: "memory");
;     __syncthreads();
;     if (wid == 0) {
;         if (lane_id() == 0) {
;             __builtin_amdgcn_s_waitcnt(0);
;             const unsigned x = xb_xcc_id();
;             unsigned nloc = st[0], nx = st[1];
;             if (nloc == 0u) { xcd_barrier_complete(bar, x, nloc, nx); st[0] = nloc; st[1] = nx; }
.Lconv_tramp_skip:
	s_cmp_gt_i32 s35, 6
	s_cselect_b64 s[2:3], -1, 0
	s_and_b64 s[4:5], s[4:5], s[2:3]
	s_andn2_b64 vcc, exec, s[4:5]
	s_cbranch_vccnz .LBB0_766
	s_load_dwordx2 s[8:9], s[0:1], 0xa8
	s_waitcnt vmcnt(0)
	s_cmp_gt_u32 s88, 63
	s_waitcnt vmcnt(0) lgkmcnt(0)
	s_barrier
	s_cbranch_scc1 .LBB0_765
	v_mbcnt_hi_u32_b32 v0, -1, v254
	s_nop 0
	v_cmp_eq_u32_e32 vcc, 0, v0
	s_and_saveexec_b64 s[4:5], vcc
	s_cbranch_execz .LBB0_764
	s_add_i32 s11, 0, 0x20000
	v_mov_b32_e32 v0, s11
	s_waitcnt vmcnt(0) expcnt(0) lgkmcnt(0)
	s_getreg_b32 s10, hwreg(HW_REG_XCC_ID, 0, 4)
	ds_read_b32 v2, v0
	s_add_i32 s11, 0, 0x20004
	v_mov_b32_e32 v0, s11
	ds_read_b32 v0, v0
	s_and_b32 s54, s10, 15
	s_waitcnt lgkmcnt(1)
	v_cmp_ne_u32_e32 vcc, 0, v2
	s_cbranch_vccnz .LBB0_728
	s_add_u32 s10, s8, 0xcd80200
	s_addc_u32 s11, s9, 0
	s_add_u32 s12, s8, 0xcd80400
	s_addc_u32 s13, s9, 0
	s_add_u32 s14, s8, 0xcd80500
	s_addc_u32 s15, s9, 0
	s_add_u32 s16, s8, 0xcd80600
	s_addc_u32 s17, s9, 0
	s_add_u32 s18, s8, 0xcd80700
	s_addc_u32 s19, s9, 0
	s_add_u32 s20, s8, 0xcd80800
	s_addc_u32 s21, s9, 0
	s_add_u32 s22, s8, 0xcd80900
	s_addc_u32 s23, s9, 0
	s_add_u32 s24, s8, 0xcd80a00
	s_addc_u32 s25, s9, 0
	s_add_u32 s26, s8, 0xcd80b00
	s_addc_u32 s27, s9, 0
	s_add_u32 s28, s8, 0xcd80c00
	s_addc_u32 s29, s9, 0
	s_add_u32 s30, s8, 0xcd80d00
	s_addc_u32 s31, s9, 0
	s_add_u32 s36, s8, 0xcd80e00
	s_addc_u32 s37, s9, 0
	s_add_u32 s38, s8, 0xcd80f00
	s_addc_u32 s39, s9, 0
	s_add_u32 s40, s8, 0xcd81000
	s_addc_u32 s41, s9, 0
	s_add_u32 s42, s8, 0xcd81100
	s_addc_u32 s43, s9, 0
	s_add_u32 s44, s8, 0xcd81200
	s_addc_u32 s45, s9, 0
	s_add_u32 s46, s8, 0xcd81300
	s_addc_u32 s47, s9, 0
	s_mov_b32 s55, 1
	v_mov_b32_e32 v16, 0
	s_branch .LBB0_716

; #define LAS __attribute__((address_space(3)))
; DI int lane_id() { int l = __builtin_amdgcn_mbcnt_hi(-1, __builtin_amdgcn_mbcnt_lo(-1, 0)); asm volatile("" : "+v"(l)); return l; }
; DI unsigned xb_ld(unsigned* q) { return __hip_atomic_load(q, __ATOMIC_RELAXED, __HIP_MEMORY_SCOPE_AGENT); }
; DI unsigned xb_xcc_id() { return (unsigned)__builtin_amdgcn_s_getreg((3 << 11) | 20) & 0xFu; }
; DI void xcd_barrier_complete(unsigned* bar, unsigned x, unsigned& nloc, unsigned& nx) {
;     ...
;         sum = 0u; cnt = 0u; mine = 0u;
; #pragma unroll
;         for (unsigned j = 0; j < 16; ++j) { const unsigned c = xb_ld(&bar[XB_XCNT(j)]); sum += c; cnt += (c > 0u) ? 1u : 0u; mine = (j == x) ? c : mine; }
; DI void grid_bar(unsigned* bar, volatile LAS unsigned* st, int wid) {
;     asm volatile("s_waitcnt vmcnt(0)" ::: "memory");
;     __syncthreads();
;     if (wid == 0) {
;         if (lane_id() == 0) {
;             __builtin_amdgcn_s_waitcnt(0);
;             const unsigned x = xb_xcc_id();
;             unsigned nloc = st[0], nx = st[1];
;             if (nloc == 0u) { xcd_barrier_complete(bar, x, nloc, nx); st[0] = nloc; st[1] = nx; }
.LBB0_805:
	s_cmp_gt_i32 s35, 7
	s_cselect_b64 s[2:3], -1, 0
	s_and_b64 s[4:5], s[8:9], s[2:3]
	s_andn2_b64 vcc, exec, s[4:5]
	s_cbranch_vccnz .LBB0_861
	s_load_dwordx2 s[8:9], s[0:1], 0xa8
	s_waitcnt vmcnt(0)
	s_cmp_gt_u32 s88, 63
	s_waitcnt vmcnt(0) lgkmcnt(0)
	s_barrier
	s_cbranch_scc1 .LBB0_860
	v_mbcnt_hi_u32_b32 v0, -1, v254
	s_nop 0
	v_cmp_eq_u32_e32 vcc, 0, v0
	s_and_saveexec_b64 s[4:5], vcc
	s_cbranch_execz .LBB0_859
	s_add_i32 s11, 0, 0x20000
	v_mov_b32_e32 v0, s11
	s_waitcnt vmcnt(0) expcnt(0) lgkmcnt(0)
	s_getreg_b32 s10, hwreg(HW_REG_XCC_ID, 0, 4)
	ds_read_b32 v2, v0
	s_add_i32 s11, 0, 0x20004
	v_mov_b32_e32 v0, s11
	ds_read_b32 v0, v0
	s_and_b32 s54, s10, 15
	s_waitcnt lgkmcnt(1)
	v_cmp_ne_u32_e32 vcc, 0, v2
	s_cbranch_vccnz .LBB0_823
	s_add_u32 s10, s8, 0xcd80200
	s_addc_u32 s11, s9, 0
	s_add_u32 s12, s8, 0xcd80400
	s_addc_u32 s13, s9, 0
	s_add_u32 s14, s8, 0xcd80500
	s_addc_u32 s15, s9, 0
	s_add_u32 s16, s8, 0xcd80600
	s_addc_u32 s17, s9, 0
	s_add_u32 s18, s8, 0xcd80700
	s_addc_u32 s19, s9, 0
	s_add_u32 s20, s8, 0xcd80800
	s_addc_u32 s21, s9, 0
	s_add_u32 s22, s8, 0xcd80900
	s_addc_u32 s23, s9, 0
	s_add_u32 s24, s8, 0xcd80a00
	s_addc_u32 s25, s9, 0
	s_add_u32 s26, s8, 0xcd80b00
	s_addc_u32 s27, s9, 0
	s_add_u32 s28, s8, 0xcd80c00
	s_addc_u32 s29, s9, 0
	s_add_u32 s30, s8, 0xcd80d00
	s_addc_u32 s31, s9, 0
	s_add_u32 s36, s8, 0xcd80e00
	s_addc_u32 s37, s9, 0
	s_add_u32 s38, s8, 0xcd80f00
	s_addc_u32 s39, s9, 0
	s_add_u32 s40, s8, 0xcd81000
	s_addc_u32 s41, s9, 0
	s_add_u32 s42, s8, 0xcd81100
	s_addc_u32 s43, s9, 0
	s_add_u32 s44, s8, 0xcd81200
	s_addc_u32 s45, s9, 0
	s_add_u32 s46, s8, 0xcd81300
	s_addc_u32 s47, s9, 0
	s_mov_b32 s55, 1
	v_mov_b32_e32 v16, 0
	s_branch .LBB0_811

; #define LAS __attribute__((address_space(3)))
; DI int lane_id() { int l = __builtin_amdgcn_mbcnt_hi(-1, __builtin_amdgcn_mbcnt_lo(-1, 0)); asm volatile("" : "+v"(l)); return l; }
; DI unsigned xb_ld(unsigned* q) { return __hip_atomic_load(q, __ATOMIC_RELAXED, __HIP_MEMORY_SCOPE_AGENT); }
; DI unsigned xb_xcc_id() { return (unsigned)__builtin_amdgcn_s_getreg((3 << 11) | 20) & 0xFu; }
; DI void xcd_barrier_complete(unsigned* bar, unsigned x, unsigned& nloc, unsigned& nx) {
;     ...
;         sum = 0u; cnt = 0u; mine = 0u;
; #pragma unroll
;         for (unsigned j = 0; j < 16; ++j) { const unsigned c = xb_ld(&bar[XB_XCNT(j)]); sum += c; cnt += (c > 0u) ? 1u : 0u; mine = (j == x) ? c : mine; }
; DI void grid_bar(unsigned* bar, volatile LAS unsigned* st, int wid) {
;     asm volatile("s_waitcnt vmcnt(0)" ::: "memory");
;     __syncthreads();
;     if (wid == 0) {
;         if (lane_id() == 0) {
;             __builtin_amdgcn_s_waitcnt(0);
;             const unsigned x = xb_xcc_id();
;             unsigned nloc = st[0], nx = st[1];
;             if (nloc == 0u) { xcd_barrier_complete(bar, x, nloc, nx); st[0] = nloc; st[1] = nx; }
.Lconv_skip_2:
	s_cmp_gt_i32 s35, 8
	s_cselect_b64 s[2:3], -1, 0
	s_and_b64 s[4:5], s[8:9], s[2:3]
	s_andn2_b64 vcc, exec, s[4:5]
	s_cbranch_vccnz .LBB0_954
	s_load_dwordx2 s[8:9], s[0:1], 0xa8
	s_waitcnt vmcnt(0)
	s_cmp_gt_u32 s88, 63
	s_waitcnt vmcnt(0) lgkmcnt(0)
	s_barrier
	s_cbranch_scc1 .LBB0_953
	v_mbcnt_hi_u32_b32 v0, -1, v254
	s_nop 0
	v_cmp_eq_u32_e32 vcc, 0, v0
	s_and_saveexec_b64 s[4:5], vcc
	s_cbranch_execz .LBB0_952
	s_add_i32 s11, 0, 0x20000
	v_mov_b32_e32 v0, s11
	s_waitcnt vmcnt(0) expcnt(0) lgkmcnt(0)
	s_getreg_b32 s10, hwreg(HW_REG_XCC_ID, 0, 4)
	ds_read_b32 v2, v0
	s_add_i32 s11, 0, 0x20004
	v_mov_b32_e32 v0, s11
	ds_read_b32 v0, v0
	s_and_b32 s54, s10, 15
	s_waitcnt lgkmcnt(1)
	v_cmp_ne_u32_e32 vcc, 0, v2
	s_cbranch_vccnz .LBB0_916
	s_add_u32 s10, s8, 0xcd80200
	s_addc_u32 s11, s9, 0
	s_add_u32 s12, s8, 0xcd80400
	s_addc_u32 s13, s9, 0
	s_add_u32 s14, s8, 0xcd80500
	s_addc_u32 s15, s9, 0
	s_add_u32 s16, s8, 0xcd80600
	s_addc_u32 s17, s9, 0
	s_add_u32 s18, s8, 0xcd80700
	s_addc_u32 s19, s9, 0
	s_add_u32 s20, s8, 0xcd80800
	s_addc_u32 s21, s9, 0
	s_add_u32 s22, s8, 0xcd80900
	s_addc_u32 s23, s9, 0
	s_add_u32 s24, s8, 0xcd80a00
	s_addc_u32 s25, s9, 0
	s_add_u32 s26, s8, 0xcd80b00
	s_addc_u32 s27, s9, 0
	s_add_u32 s28, s8, 0xcd80c00
	s_addc_u32 s29, s9, 0
	s_add_u32 s30, s8, 0xcd80d00
	s_addc_u32 s31, s9, 0
	s_add_u32 s36, s8, 0xcd80e00
	s_addc_u32 s37, s9, 0
	s_add_u32 s38, s8, 0xcd80f00
	s_addc_u32 s39, s9, 0
	s_add_u32 s40, s8, 0xcd81000
	s_addc_u32 s41, s9, 0
	s_add_u32 s42, s8, 0xcd81100
	s_addc_u32 s43, s9, 0
	s_add_u32 s44, s8, 0xcd81200
	s_addc_u32 s45, s9, 0
	s_add_u32 s46, s8, 0xcd81300
	s_addc_u32 s47, s9, 0
	s_mov_b32 s55, 1
	v_mov_b32_e32 v16, 0
	s_branch .LBB0_904

; #define LAS __attribute__((address_space(3)))
; DI int lane_id() { int l = __builtin_amdgcn_mbcnt_hi(-1, __builtin_amdgcn_mbcnt_lo(-1, 0)); asm volatile("" : "+v"(l)); return l; }
; DI unsigned xb_ld(unsigned* q) { return __hip_atomic_load(q, __ATOMIC_RELAXED, __HIP_MEMORY_SCOPE_AGENT); }
; DI unsigned xb_xcc_id() { return (unsigned)__builtin_amdgcn_s_getreg((3 << 11) | 20) & 0xFu; }
; DI void xcd_barrier_complete(unsigned* bar, unsigned x, unsigned& nloc, unsigned& nx) {
;     ...
;         sum = 0u; cnt = 0u; mine = 0u;
; #pragma unroll
;         for (unsigned j = 0; j < 16; ++j) { const unsigned c = xb_ld(&bar[XB_XCNT(j)]); sum += c; cnt += (c > 0u) ? 1u : 0u; mine = (j == x) ? c : mine; }
; DI void grid_bar(unsigned* bar, volatile LAS unsigned* st, int wid) {
;     asm volatile("s_waitcnt vmcnt(0)" ::: "memory");
;     __syncthreads();
;     if (wid == 0) {
;         if (lane_id() == 0) {
;             __builtin_amdgcn_s_waitcnt(0);
;             const unsigned x = xb_xcc_id();
;             unsigned nloc = st[0], nx = st[1];
;             if (nloc == 0u) { xcd_barrier_complete(bar, x, nloc, nx); st[0] = nloc; st[1] = nx; }
.Lconv_skip_3:
	s_cmp_gt_i32 s35, 9
	s_cselect_b64 s[4:5], -1, 0
	s_and_b64 s[2:3], s[2:3], s[4:5]
	s_andn2_b64 vcc, exec, s[2:3]
	s_cbranch_vccnz .LBB0_1073
	s_load_dwordx2 s[8:9], s[0:1], 0xa8
	s_waitcnt vmcnt(0)
	s_cmp_gt_u32 s88, 63
	s_waitcnt vmcnt(0) lgkmcnt(0)
	s_barrier
	s_cbranch_scc1 .LBB0_1072
	v_mbcnt_hi_u32_b32 v0, -1, v254
	s_nop 0
	v_cmp_eq_u32_e32 vcc, 0, v0
	s_and_saveexec_b64 s[2:3], vcc
	s_cbranch_execz .LBB0_1071
	s_add_i32 s11, 0, 0x20000
	v_mov_b32_e32 v0, s11
	s_waitcnt vmcnt(0) expcnt(0) lgkmcnt(0)
	s_getreg_b32 s10, hwreg(HW_REG_XCC_ID, 0, 4)
	ds_read_b32 v2, v0
	s_add_i32 s11, 0, 0x20004
	v_mov_b32_e32 v0, s11
	ds_read_b32 v0, v0
	s_and_b32 s54, s10, 15
	s_waitcnt lgkmcnt(1)
	v_cmp_ne_u32_e32 vcc, 0, v2
	s_cbranch_vccnz .LBB0_1035
	s_add_u32 s10, s8, 0xcd80200
	s_addc_u32 s11, s9, 0
	s_add_u32 s12, s8, 0xcd80400
	s_addc_u32 s13, s9, 0
	s_add_u32 s14, s8, 0xcd80500
	s_addc_u32 s15, s9, 0
	s_add_u32 s16, s8, 0xcd80600
	s_addc_u32 s17, s9, 0
	s_add_u32 s18, s8, 0xcd80700
	s_addc_u32 s19, s9, 0
	s_add_u32 s20, s8, 0xcd80800
	s_addc_u32 s21, s9, 0
	s_add_u32 s22, s8, 0xcd80900
	s_addc_u32 s23, s9, 0
	s_add_u32 s24, s8, 0xcd80a00
	s_addc_u32 s25, s9, 0
	s_add_u32 s26, s8, 0xcd80b00
	s_addc_u32 s27, s9, 0
	s_add_u32 s28, s8, 0xcd80c00
	s_addc_u32 s29, s9, 0
	s_add_u32 s30, s8, 0xcd80d00
	s_addc_u32 s31, s9, 0
	s_add_u32 s36, s8, 0xcd80e00
	s_addc_u32 s37, s9, 0
	s_add_u32 s38, s8, 0xcd80f00
	s_addc_u32 s39, s9, 0
	s_add_u32 s40, s8, 0xcd81000
	s_addc_u32 s41, s9, 0
	s_add_u32 s42, s8, 0xcd81100
	s_addc_u32 s43, s9, 0
	s_add_u32 s44, s8, 0xcd81200
	s_addc_u32 s45, s9, 0
	s_add_u32 s46, s8, 0xcd81300
	s_addc_u32 s47, s9, 0
	s_mov_b32 s55, 1
	v_mov_b32_e32 v16, 0
	s_branch .LBB0_1023

; #define LAS __attribute__((address_space(3)))
; DI int lane_id() { int l = __builtin_amdgcn_mbcnt_hi(-1, __builtin_amdgcn_mbcnt_lo(-1, 0)); asm volatile("" : "+v"(l)); return l; }
; DI unsigned xb_ld(unsigned* q) { return __hip_atomic_load(q, __ATOMIC_RELAXED, __HIP_MEMORY_SCOPE_AGENT); }
; DI unsigned xb_xcc_id() { return (unsigned)__builtin_amdgcn_s_getreg((3 << 11) | 20) & 0xFu; }
; DI void xcd_barrier_complete(unsigned* bar, unsigned x, unsigned& nloc, unsigned& nx) {
;     ...
;         sum = 0u; cnt = 0u; mine = 0u;
; #pragma unroll
;         for (unsigned j = 0; j < 16; ++j) { const unsigned c = xb_ld(&bar[XB_XCNT(j)]); sum += c; cnt += (c > 0u) ? 1u : 0u; mine = (j == x) ? c : mine; }
; DI void grid_bar(unsigned* bar, volatile LAS unsigned* st, int wid) {
;     asm volatile("s_waitcnt vmcnt(0)" ::: "memory");
;     __syncthreads();
;     if (wid == 0) {
;         if (lane_id() == 0) {
;             __builtin_amdgcn_s_waitcnt(0);
;             const unsigned x = xb_xcc_id();
;             unsigned nloc = st[0], nx = st[1];
;             if (nloc == 0u) { xcd_barrier_complete(bar, x, nloc, nx); st[0] = nloc; st[1] = nx; }
.LBB0_1101:
	s_cmp_gt_i32 s35, 10
	s_cselect_b64 s[4:5], -1, 0
	s_and_b64 s[2:3], s[2:3], s[4:5]
	s_andn2_b64 vcc, exec, s[2:3]
	s_cbranch_vccnz .LBB0_1157
	s_load_dwordx2 s[8:9], s[0:1], 0xa8
	s_waitcnt vmcnt(0)
	s_cmp_gt_u32 s88, 63
	s_waitcnt vmcnt(0) lgkmcnt(0)
	s_barrier
	s_cbranch_scc1 .LBB0_1156
	v_mbcnt_hi_u32_b32 v0, -1, v254
	s_nop 0
	v_cmp_eq_u32_e32 vcc, 0, v0
	s_and_saveexec_b64 s[2:3], vcc
	s_cbranch_execz .LBB0_1155
	s_add_i32 s11, 0, 0x20000
	v_mov_b32_e32 v0, s11
	s_waitcnt vmcnt(0) expcnt(0) lgkmcnt(0)
	s_getreg_b32 s10, hwreg(HW_REG_XCC_ID, 0, 4)
	ds_read_b32 v2, v0
	s_add_i32 s11, 0, 0x20004
	v_mov_b32_e32 v0, s11
	ds_read_b32 v0, v0
	s_and_b32 s54, s10, 15
	s_waitcnt lgkmcnt(1)
	v_cmp_ne_u32_e32 vcc, 0, v2
	s_cbranch_vccnz .LBB0_1119
	s_add_u32 s10, s8, 0xcd80200
	s_addc_u32 s11, s9, 0
	s_add_u32 s12, s8, 0xcd80400
	s_addc_u32 s13, s9, 0
	s_add_u32 s14, s8, 0xcd80500
	s_addc_u32 s15, s9, 0
	s_add_u32 s16, s8, 0xcd80600
	s_addc_u32 s17, s9, 0
	s_add_u32 s18, s8, 0xcd80700
	s_addc_u32 s19, s9, 0
	s_add_u32 s20, s8, 0xcd80800
	s_addc_u32 s21, s9, 0
	s_add_u32 s22, s8, 0xcd80900
	s_addc_u32 s23, s9, 0
	s_add_u32 s24, s8, 0xcd80a00
	s_addc_u32 s25, s9, 0
	s_add_u32 s26, s8, 0xcd80b00
	s_addc_u32 s27, s9, 0
	s_add_u32 s28, s8, 0xcd80c00
	s_addc_u32 s29, s9, 0
	s_add_u32 s30, s8, 0xcd80d00
	s_addc_u32 s31, s9, 0
	s_add_u32 s36, s8, 0xcd80e00
	s_addc_u32 s37, s9, 0
	s_add_u32 s38, s8, 0xcd80f00
	s_addc_u32 s39, s9, 0
	s_add_u32 s40, s8, 0xcd81000
	s_addc_u32 s41, s9, 0
	s_add_u32 s42, s8, 0xcd81100
	s_addc_u32 s43, s9, 0
	s_add_u32 s44, s8, 0xcd81200
	s_addc_u32 s45, s9, 0
	s_add_u32 s46, s8, 0xcd81300
	s_addc_u32 s47, s9, 0
	s_mov_b32 s55, 1
	v_mov_b32_e32 v16, 0
	s_branch .LBB0_1107

; #define LAS __attribute__((address_space(3)))
; DI int lane_id() { int l = __builtin_amdgcn_mbcnt_hi(-1, __builtin_amdgcn_mbcnt_lo(-1, 0)); asm volatile("" : "+v"(l)); return l; }
; DI unsigned xb_ld(unsigned* q) { return __hip_atomic_load(q, __ATOMIC_RELAXED, __HIP_MEMORY_SCOPE_AGENT); }
; DI unsigned xb_xcc_id() { return (unsigned)__builtin_amdgcn_s_getreg((3 << 11) | 20) & 0xFu; }
; DI void xcd_barrier_complete(unsigned* bar, unsigned x, unsigned& nloc, unsigned& nx) {
;     ...
;         sum = 0u; cnt = 0u; mine = 0u;
; #pragma unroll
;         for (unsigned j = 0; j < 16; ++j) { const unsigned c = xb_ld(&bar[XB_XCNT(j)]); sum += c; cnt += (c > 0u) ? 1u : 0u; mine = (j == x) ? c : mine; }
; DI void grid_bar(unsigned* bar, volatile LAS unsigned* st, int wid) {
;     asm volatile("s_waitcnt vmcnt(0)" ::: "memory");
;     __syncthreads();
;     if (wid == 0) {
;         if (lane_id() == 0) {
;             __builtin_amdgcn_s_waitcnt(0);
;             const unsigned x = xb_xcc_id();
;             unsigned nloc = st[0], nx = st[1];
;             if (nloc == 0u) { xcd_barrier_complete(bar, x, nloc, nx); st[0] = nloc; st[1] = nx; }
.LBB0_1196:
	s_cmp_gt_i32 s35, 11
	s_cselect_b64 s[2:3], -1, 0
	s_and_b64 s[4:5], s[8:9], s[2:3]
	s_andn2_b64 vcc, exec, s[4:5]
	s_cbranch_vccnz .LBB0_1252
	s_load_dwordx2 s[8:9], s[0:1], 0xa8
	s_waitcnt vmcnt(0)
	s_cmp_gt_u32 s88, 63
	s_waitcnt vmcnt(0) lgkmcnt(0)
	s_barrier
	s_cbranch_scc1 .LBB0_1251
	v_mbcnt_hi_u32_b32 v0, -1, v254
	s_nop 0
	v_cmp_eq_u32_e32 vcc, 0, v0
	s_and_saveexec_b64 s[4:5], vcc
	s_cbranch_execz .LBB0_1250
	s_add_i32 s11, 0, 0x20000
	v_mov_b32_e32 v0, s11
	s_waitcnt vmcnt(0) expcnt(0) lgkmcnt(0)
	s_getreg_b32 s10, hwreg(HW_REG_XCC_ID, 0, 4)
	ds_read_b32 v2, v0
	s_add_i32 s11, 0, 0x20004
	v_mov_b32_e32 v0, s11
	ds_read_b32 v0, v0
	s_and_b32 s54, s10, 15
	s_waitcnt lgkmcnt(1)
	v_cmp_ne_u32_e32 vcc, 0, v2
	s_cbranch_vccnz .LBB0_1214
	s_add_u32 s10, s8, 0xcd80200
	s_addc_u32 s11, s9, 0
	s_add_u32 s12, s8, 0xcd80400
	s_addc_u32 s13, s9, 0
	s_add_u32 s14, s8, 0xcd80500
	s_addc_u32 s15, s9, 0
	s_add_u32 s16, s8, 0xcd80600
	s_addc_u32 s17, s9, 0
	s_add_u32 s18, s8, 0xcd80700
	s_addc_u32 s19, s9, 0
	s_add_u32 s20, s8, 0xcd80800
	s_addc_u32 s21, s9, 0
	s_add_u32 s22, s8, 0xcd80900
	s_addc_u32 s23, s9, 0
	s_add_u32 s24, s8, 0xcd80a00
	s_addc_u32 s25, s9, 0
	s_add_u32 s26, s8, 0xcd80b00
	s_addc_u32 s27, s9, 0
	s_add_u32 s28, s8, 0xcd80c00
	s_addc_u32 s29, s9, 0
	s_add_u32 s30, s8, 0xcd80d00
	s_addc_u32 s31, s9, 0
	s_add_u32 s36, s8, 0xcd80e00
	s_addc_u32 s37, s9, 0
	s_add_u32 s38, s8, 0xcd80f00
	s_addc_u32 s39, s9, 0
	s_add_u32 s40, s8, 0xcd81000
	s_addc_u32 s41, s9, 0
	s_add_u32 s42, s8, 0xcd81100
	s_addc_u32 s43, s9, 0
	s_add_u32 s44, s8, 0xcd81200
	s_addc_u32 s45, s9, 0
	s_add_u32 s46, s8, 0xcd81300
	s_addc_u32 s47, s9, 0
	s_mov_b32 s55, 1
	v_mov_b32_e32 v16, 0
	s_branch .LBB0_1202

; #define LAS __attribute__((address_space(3)))
; DI int lane_id() { int l = __builtin_amdgcn_mbcnt_hi(-1, __builtin_amdgcn_mbcnt_lo(-1, 0)); asm volatile("" : "+v"(l)); return l; }
; DI unsigned xb_ld(unsigned* q) { return __hip_atomic_load(q, __ATOMIC_RELAXED, __HIP_MEMORY_SCOPE_AGENT); }
; DI unsigned xb_xcc_id() { return (unsigned)__builtin_amdgcn_s_getreg((3 << 11) | 20) & 0xFu; }
; DI void xcd_barrier_complete(unsigned* bar, unsigned x, unsigned& nloc, unsigned& nx) {
;     ...
;         sum = 0u; cnt = 0u; mine = 0u;
; #pragma unroll
;         for (unsigned j = 0; j < 16; ++j) { const unsigned c = xb_ld(&bar[XB_XCNT(j)]); sum += c; cnt += (c > 0u) ? 1u : 0u; mine = (j == x) ? c : mine; }
; DI void grid_bar(unsigned* bar, volatile LAS unsigned* st, int wid) {
;     asm volatile("s_waitcnt vmcnt(0)" ::: "memory");
;     __syncthreads();
;     if (wid == 0) {
;         if (lane_id() == 0) {
;             __builtin_amdgcn_s_waitcnt(0);
;             const unsigned x = xb_xcc_id();
;             unsigned nloc = st[0], nx = st[1];
;             if (nloc == 0u) { xcd_barrier_complete(bar, x, nloc, nx); st[0] = nloc; st[1] = nx; }
.Lconv_skip_4:
	s_cmp_gt_i32 s35, 12
	s_cselect_b64 s[2:3], -1, 0
	s_and_b64 s[4:5], s[4:5], s[2:3]
	s_andn2_b64 vcc, exec, s[4:5]
	s_cbranch_vccnz .LBB0_1321
	s_load_dwordx2 s[8:9], s[0:1], 0xa8
	s_waitcnt vmcnt(0)
	s_cmp_gt_u32 s88, 63
	s_waitcnt vmcnt(0) lgkmcnt(0)
	s_barrier
	s_cbranch_scc1 .LBB0_1320
	v_mbcnt_hi_u32_b32 v0, -1, v254
	s_nop 0
	v_cmp_eq_u32_e32 vcc, 0, v0
	s_and_saveexec_b64 s[4:5], vcc
	s_cbranch_execz .LBB0_1319
	s_add_i32 s11, 0, 0x20000
	v_mov_b32_e32 v0, s11
	s_waitcnt vmcnt(0) expcnt(0) lgkmcnt(0)
	s_getreg_b32 s10, hwreg(HW_REG_XCC_ID, 0, 4)
	ds_read_b32 v2, v0
	s_add_i32 s11, 0, 0x20004
	v_mov_b32_e32 v0, s11
	ds_read_b32 v0, v0
	s_and_b32 s54, s10, 15
	s_waitcnt lgkmcnt(1)
	v_cmp_ne_u32_e32 vcc, 0, v2
	s_cbranch_vccnz .LBB0_1283
	s_add_u32 s10, s8, 0xcd80200
	s_addc_u32 s11, s9, 0
	s_add_u32 s12, s8, 0xcd80400
	s_addc_u32 s13, s9, 0
	s_add_u32 s14, s8, 0xcd80500
	s_addc_u32 s15, s9, 0
	s_add_u32 s16, s8, 0xcd80600
	s_addc_u32 s17, s9, 0
	s_add_u32 s18, s8, 0xcd80700
	s_addc_u32 s19, s9, 0
	s_add_u32 s20, s8, 0xcd80800
	s_addc_u32 s21, s9, 0
	s_add_u32 s22, s8, 0xcd80900
	s_addc_u32 s23, s9, 0
	s_add_u32 s24, s8, 0xcd80a00
	s_addc_u32 s25, s9, 0
	s_add_u32 s26, s8, 0xcd80b00
	s_addc_u32 s27, s9, 0
	s_add_u32 s28, s8, 0xcd80c00
	s_addc_u32 s29, s9, 0
	s_add_u32 s30, s8, 0xcd80d00
	s_addc_u32 s31, s9, 0
	s_add_u32 s36, s8, 0xcd80e00
	s_addc_u32 s37, s9, 0
	s_add_u32 s38, s8, 0xcd80f00
	s_addc_u32 s39, s9, 0
	s_add_u32 s40, s8, 0xcd81000
	s_addc_u32 s41, s9, 0
	s_add_u32 s42, s8, 0xcd81100
	s_addc_u32 s43, s9, 0
	s_add_u32 s44, s8, 0xcd81200
	s_addc_u32 s45, s9, 0
	s_add_u32 s46, s8, 0xcd81300
	s_addc_u32 s47, s9, 0
	s_mov_b32 s55, 1
	v_mov_b32_e32 v16, 0
	s_branch .LBB0_1271

; #define LAS __attribute__((address_space(3)))
; DI int lane_id() { int l = __builtin_amdgcn_mbcnt_hi(-1, __builtin_amdgcn_mbcnt_lo(-1, 0)); asm volatile("" : "+v"(l)); return l; }
; DI unsigned xb_ld(unsigned* q) { return __hip_atomic_load(q, __ATOMIC_RELAXED, __HIP_MEMORY_SCOPE_AGENT); }
; DI unsigned xb_xcc_id() { return (unsigned)__builtin_amdgcn_s_getreg((3 << 11) | 20) & 0xFu; }
; DI void xcd_barrier_complete(unsigned* bar, unsigned x, unsigned& nloc, unsigned& nx) {
;     ...
;         sum = 0u; cnt = 0u; mine = 0u;
; #pragma unroll
;         for (unsigned j = 0; j < 16; ++j) { const unsigned c = xb_ld(&bar[XB_XCNT(j)]); sum += c; cnt += (c > 0u) ? 1u : 0u; mine = (j == x) ? c : mine; }
; DI void grid_bar(unsigned* bar, volatile LAS unsigned* st, int wid) {
;     asm volatile("s_waitcnt vmcnt(0)" ::: "memory");
;     __syncthreads();
;     if (wid == 0) {
;         if (lane_id() == 0) {
;             __builtin_amdgcn_s_waitcnt(0);
;             const unsigned x = xb_xcc_id();
;             unsigned nloc = st[0], nx = st[1];
;             if (nloc == 0u) { xcd_barrier_complete(bar, x, nloc, nx); st[0] = nloc; st[1] = nx; }
.LBB0_1360:
	s_cmp_gt_i32 s35, 13
	s_cselect_b64 s[2:3], -1, 0
	s_and_b64 s[4:5], s[8:9], s[2:3]
	s_andn2_b64 vcc, exec, s[4:5]
	s_cbranch_vccnz .LBB0_1416
	s_load_dwordx2 s[8:9], s[0:1], 0xa8
	s_waitcnt vmcnt(0)
	s_cmp_gt_u32 s88, 63
	s_waitcnt vmcnt(0) lgkmcnt(0)
	s_barrier
	s_cbranch_scc1 .LBB0_1415
	v_mbcnt_hi_u32_b32 v0, -1, v254
	s_nop 0
	v_cmp_eq_u32_e32 vcc, 0, v0
	s_and_saveexec_b64 s[4:5], vcc
	s_cbranch_execz .LBB0_1414
	s_add_i32 s11, 0, 0x20000
	v_mov_b32_e32 v0, s11
	s_waitcnt vmcnt(0) expcnt(0) lgkmcnt(0)
	s_getreg_b32 s10, hwreg(HW_REG_XCC_ID, 0, 4)
	ds_read_b32 v2, v0
	s_add_i32 s11, 0, 0x20004
	v_mov_b32_e32 v0, s11
	ds_read_b32 v0, v0
	s_and_b32 s35, s10, 15
	s_waitcnt lgkmcnt(1)
	v_cmp_ne_u32_e32 vcc, 0, v2
	s_cbranch_vccnz .LBB0_1378
	s_add_u32 s10, s8, 0xcd80200
	s_addc_u32 s11, s9, 0
	s_add_u32 s12, s8, 0xcd80400
	s_addc_u32 s13, s9, 0
	s_add_u32 s14, s8, 0xcd80500
	s_addc_u32 s15, s9, 0
	s_add_u32 s16, s8, 0xcd80600
	s_addc_u32 s17, s9, 0
	s_add_u32 s18, s8, 0xcd80700
	s_addc_u32 s19, s9, 0
	s_add_u32 s20, s8, 0xcd80800
	s_addc_u32 s21, s9, 0
	s_add_u32 s22, s8, 0xcd80900
	s_addc_u32 s23, s9, 0
	s_add_u32 s24, s8, 0xcd80a00
	s_addc_u32 s25, s9, 0
	s_add_u32 s26, s8, 0xcd80b00
	s_addc_u32 s27, s9, 0
	s_add_u32 s28, s8, 0xcd80c00
	s_addc_u32 s29, s9, 0
	s_add_u32 s30, s8, 0xcd80d00
	s_addc_u32 s31, s9, 0
	s_add_u32 s36, s8, 0xcd80e00
	s_addc_u32 s37, s9, 0
	s_add_u32 s38, s8, 0xcd80f00
	s_addc_u32 s39, s9, 0
	s_add_u32 s40, s8, 0xcd81000
	s_addc_u32 s41, s9, 0
	s_add_u32 s42, s8, 0xcd81100
	s_addc_u32 s43, s9, 0
	s_add_u32 s44, s8, 0xcd81200
	s_addc_u32 s45, s9, 0
	s_add_u32 s46, s8, 0xcd81300
	s_addc_u32 s47, s9, 0
	s_mov_b32 s54, 1
	v_mov_b32_e32 v16, 0
	s_branch .LBB0_1366
